# pool items: staging loads issued before the 32 weight-fragment loads; staging wait is vmcnt(32) so the weights stay in flight under staging and window sums
# speedup vs baseline: 1.0208x; 1.0078x over previous
.LBB0_1225:
	v_readlane_b32 s18, v255, 4
	s_lshl_b32 s16, s18, 17
	v_readlane_b32 s2, v253, 20
	v_mov_b32_e32 v164, v218
	s_or_b32 s2, s2, s16
	v_readlane_b32 s8, v252, 29
	s_add_u32 s8, s8, s2
	v_and_b32_e32 v165, 15, v164
	v_readlane_b32 s2, v252, 30
	v_bfe_u32 v163, v164, 4, 2
	s_addc_u32 s9, s2, 0
	v_lshlrev_b32_e32 v32, 8, v165
	v_lshl_add_u64 v[0:1], s[8:9], 0, v[32:33]
	v_lshlrev_b32_e32 v32, 4, v163
	v_lshl_add_u64 v[0:1], v[0:1], 0, v[32:33]
	v_readlane_b32 s8, v253, 23
	v_readlane_b32 s9, v253, 24
	v_lshlrev_b32_e32 v130, 4, v165
	v_mov_b32_e32 v131, v33
	s_nop 1
	v_lshl_add_u64 v[136:137], s[8:9], 0, v[130:131]
	v_add_u32_e32 v134, 0, v130
	s_movk_i32 s2, 0x8f0
	v_cmp_gt_i32_e32 vcc, s2, v164
	v_readlane_b32 s19, v255, 5
	s_and_saveexec_b64 s[10:11], vcc
	v_readlane_b32 s2, v253, 25
	s_cbranch_execz .LBB0_1229
	v_ashrrev_i32_e32 v135, 4, v164
	v_cmp_lt_i32_e32 vcc, s2, v135
	v_mov_b32_e32 v232, 0
	v_mov_b32_e32 v233, 0
	v_mov_b32_e32 v234, 0
	v_mov_b32_e32 v235, 0
	s_and_saveexec_b64 s[14:15], vcc
	s_cbranch_execz .LBB0_1228
	v_readlane_b32 s8, v253, 31
	s_nop 1
	v_add_u32_e32 v232, s8, v135
	v_mad_i64_i32 v[232:233], s[8:9], v232, s70, v[136:137]
	global_load_dwordx4 v[232:235], v[232:233], off

.LBB0_1245:
	s_or_b64 exec, exec, s[10:11]
	s_movk_i32 s2, 0x1000
	v_add_co_u32_e32 v2, vcc, s2, v0
	s_movk_i32 s2, 0x3000
	s_nop 0
	v_addc_co_u32_e32 v3, vcc, 0, v1, vcc
	v_add_co_u32_e32 v126, vcc, s1, v0
	global_load_dwordx4 v[122:125], v[0:1], off
	global_load_dwordx4 v[118:121], v[0:1], off offset:64
	global_load_dwordx4 v[114:117], v[0:1], off offset:128
	global_load_dwordx4 v[110:113], v[0:1], off offset:192
	v_addc_co_u32_e32 v127, vcc, 0, v1, vcc
	v_add_co_u32_e32 v4, vcc, s2, v0
	s_movk_i32 s2, 0x4000
	s_nop 0
	v_addc_co_u32_e32 v5, vcc, 0, v1, vcc
	v_add_co_u32_e32 v6, vcc, s2, v0
	s_movk_i32 s2, 0x5000
	s_nop 0
	v_addc_co_u32_e32 v7, vcc, 0, v1, vcc
	global_load_dwordx4 v[106:109], v[2:3], off offset:64
	global_load_dwordx4 v[102:105], v[2:3], off offset:128
	global_load_dwordx4 v[98:101], v[126:127], off
	global_load_dwordx4 v[94:97], v[126:127], off offset:64
	global_load_dwordx4 v[90:93], v[126:127], off offset:128
	global_load_dwordx4 v[24:27], v[126:127], off offset:192
	global_load_dwordx4 v[28:31], v[2:3], off offset:192
	global_load_dwordx4 v[82:85], v[4:5], off offset:64
	global_load_dwordx4 v[78:81], v[4:5], off offset:128
	global_load_dwordx4 v[16:19], v[4:5], off offset:192
	global_load_dwordx4 v[86:89], v[6:7], off offset:-4096
	global_load_dwordx4 v[74:77], v[6:7], off
	global_load_dwordx4 v[70:73], v[6:7], off offset:64
	global_load_dwordx4 v[66:69], v[6:7], off offset:128
	v_add_co_u32_e32 v2, vcc, s2, v0
	s_movk_i32 s2, 0x6000
	s_nop 0
	v_addc_co_u32_e32 v3, vcc, 0, v1, vcc
	v_add_co_u32_e32 v4, vcc, s2, v0
	v_readlane_b32 s8, v253, 23
	s_nop 0
	v_addc_co_u32_e32 v5, vcc, 0, v1, vcc
	global_load_dwordx4 v[20:23], v[6:7], off offset:192
	global_load_dwordx4 v[62:65], v[4:5], off offset:-4096
	global_load_dwordx4 v[58:61], v[2:3], off offset:64
	global_load_dwordx4 v[54:57], v[2:3], off offset:128
	global_load_dwordx4 v[50:53], v[4:5], off
	global_load_dwordx4 v[46:49], v[4:5], off offset:64
	global_load_dwordx4 v[42:45], v[4:5], off offset:128
	global_load_dwordx4 v[8:11], v[4:5], off offset:192
	v_add_co_u32_e32 v0, vcc, 0x7000, v0
	v_lshlrev_b32_e32 v130, 4, v165
	s_nop 0
	v_addc_co_u32_e32 v1, vcc, 0, v1, vcc
	global_load_dwordx4 v[12:15], v[2:3], off offset:192
	global_load_dwordx4 v[38:41], v[0:1], off
	global_load_dwordx4 v[34:37], v[0:1], off offset:64
	global_load_dwordx4 v[4:7], v[0:1], off offset:128
	s_nop 0
	global_load_dwordx4 v[126:129], v[126:127], off offset:-4096
	s_nop 0
	global_load_dwordx4 v[0:3], v[0:1], off offset:192
	v_mov_b32_e32 v131, v33
	v_readlane_b32 s9, v253, 24
	s_movk_i32 s2, 0x8f0
	v_readfirstlane_b32 s17, v164
	v_lshl_add_u64 v[136:137], s[8:9], 0, v[130:131]
	v_add_u32_e32 v134, 0, v130
	s_waitcnt vmcnt(32)
	s_movk_i32 s8, 0x8f0
	v_cmp_gt_i32_e32 vcc, s8, v164
	s_and_saveexec_b64 s[10:11], vcc
	ds_write_b128 v204, v[232:235]
	s_or_b64 exec, exec, s[10:11]
	s_movk_i32 s8, 0x6f0
	v_cmp_gt_i32_e32 vcc, s8, v164
	s_and_saveexec_b64 s[10:11], vcc
	ds_write_b128 v205, v[188:191]
	s_or_b64 exec, exec, s[10:11]
	s_movk_i32 s8, 0x4f0
	v_cmp_gt_i32_e32 vcc, s8, v164
	s_and_saveexec_b64 s[10:11], vcc
	ds_write_b128 v206, v[192:195]
	s_or_b64 exec, exec, s[10:11]
	s_movk_i32 s8, 0x2f0
	v_cmp_gt_i32_e32 vcc, s8, v164
	s_and_saveexec_b64 s[10:11], vcc
	ds_write_b128 v207, v[196:199]
	s_or_b64 exec, exec, s[10:11]
	s_movk_i32 s8, 0xf0
	v_cmp_gt_i32_e32 vcc, s8, v164
	s_and_saveexec_b64 s[10:11], vcc
	ds_write_b128 v208, v[200:203]
	s_or_b64 exec, exec, s[10:11]
	v_ashrrev_i32_e32 v168, 2, v164
	v_lshlrev_b32_e32 v130, 6, v164
	v_mul_lo_u32 v166, v168, s33
	v_and_b32_e32 v167, 0xc0, v130
	v_readlane_b32 s2, v254, 56
	v_mov_b32_e32 v130, 0
	v_mov_b32_e32 v131, v130
	v_add3_u32 v169, v166, v167, s2
	v_readlane_b32 s2, v253, 19
	v_mov_b32_e32 v160, v130
	v_mov_b32_e32 v161, v130
	v_mov_b32_e32 v158, v130
	v_mov_b32_e32 v159, v130
	v_mov_b32_e32 v156, v130
	v_mov_b32_e32 v157, v130
	v_mov_b32_e32 v154, v130
	v_mov_b32_e32 v155, v130
	v_mov_b32_e32 v152, v130
	v_mov_b32_e32 v153, v130
	v_mov_b32_e32 v150, v130
	v_mov_b32_e32 v151, v130
	v_mov_b32_e32 v148, v130
	v_mov_b32_e32 v149, v130
	v_mov_b32_e32 v146, v130
	v_mov_b32_e32 v147, v130
	v_mov_b32_e32 v144, v130
	v_mov_b32_e32 v145, v130
	v_mov_b32_e32 v142, v130
	v_mov_b32_e32 v143, v130
	v_mov_b32_e32 v140, v130
	v_mov_b32_e32 v141, v130
	v_mov_b32_e32 v138, v130
	v_mov_b32_e32 v139, v130
	v_mov_b32_e32 v136, v130
	v_mov_b32_e32 v137, v130
	v_mov_b32_e32 v134, v130
	v_mov_b32_e32 v135, v130
	v_mov_b32_e32 v132, v130
	v_mov_b32_e32 v133, v130
	s_waitcnt lgkmcnt(0)
	s_barrier
.LBB0_1246:
	ds_read_b128 v[170:173], v169
	ds_read_b128 v[174:177], v169 offset:16
	ds_read_b128 v[178:181], v169 offset:32
	ds_read_b128 v[182:185], v169 offset:48
	s_add_i32 s2, s2, -1
	s_waitcnt lgkmcnt(3)
	v_lshlrev_b32_e32 v186, 16, v170
	v_and_b32_e32 v187, 0xffff0000, v170
	v_lshlrev_b32_e32 v170, 16, v171
	v_and_b32_e32 v171, 0xffff0000, v171
	v_pk_add_f32 v[158:159], v[158:159], v[170:171]
	v_lshlrev_b32_e32 v170, 16, v172
	v_and_b32_e32 v171, 0xffff0000, v172
	v_pk_add_f32 v[156:157], v[156:157], v[170:171]
	v_lshlrev_b32_e32 v170, 16, v173
	v_and_b32_e32 v171, 0xffff0000, v173
	v_pk_add_f32 v[154:155], v[154:155], v[170:171]
	s_waitcnt lgkmcnt(2)
	v_lshlrev_b32_e32 v170, 16, v174
	v_and_b32_e32 v171, 0xffff0000, v174
	v_pk_add_f32 v[152:153], v[152:153], v[170:171]
	v_lshlrev_b32_e32 v170, 16, v175
	v_and_b32_e32 v171, 0xffff0000, v175
	v_pk_add_f32 v[150:151], v[150:151], v[170:171]
	v_lshlrev_b32_e32 v170, 16, v176
	v_and_b32_e32 v171, 0xffff0000, v176
	v_pk_add_f32 v[148:149], v[148:149], v[170:171]
	v_lshlrev_b32_e32 v170, 16, v177
	v_and_b32_e32 v171, 0xffff0000, v177
	v_pk_add_f32 v[146:147], v[146:147], v[170:171]
	s_waitcnt lgkmcnt(1)
	v_lshlrev_b32_e32 v170, 16, v178
	v_and_b32_e32 v171, 0xffff0000, v178
	v_pk_add_f32 v[144:145], v[144:145], v[170:171]
	v_lshlrev_b32_e32 v170, 16, v179
	v_and_b32_e32 v171, 0xffff0000, v179
	v_pk_add_f32 v[142:143], v[142:143], v[170:171]
	v_lshlrev_b32_e32 v170, 16, v180
	v_and_b32_e32 v171, 0xffff0000, v180
	v_pk_add_f32 v[140:141], v[140:141], v[170:171]
	v_lshlrev_b32_e32 v170, 16, v181
	v_and_b32_e32 v171, 0xffff0000, v181
	v_pk_add_f32 v[138:139], v[138:139], v[170:171]
	s_waitcnt lgkmcnt(0)
	v_lshlrev_b32_e32 v170, 16, v182
	v_and_b32_e32 v171, 0xffff0000, v182
	v_pk_add_f32 v[136:137], v[136:137], v[170:171]
	v_lshlrev_b32_e32 v170, 16, v183
	v_and_b32_e32 v171, 0xffff0000, v183
	v_pk_add_f32 v[134:135], v[134:135], v[170:171]
	v_lshlrev_b32_e32 v170, 16, v184
	v_and_b32_e32 v171, 0xffff0000, v184
	v_pk_add_f32 v[132:133], v[132:133], v[170:171]
	v_lshlrev_b32_e32 v170, 16, v185
	v_and_b32_e32 v171, 0xffff0000, v185
	v_pk_add_f32 v[160:161], v[160:161], v[186:187]
	v_pk_add_f32 v[130:131], v[130:131], v[170:171]
	v_add_u32_e32 v169, 0xfffffef0, v169
	s_cmp_lg_u32 s2, 0
	s_cbranch_scc1 .LBB0_1246
	v_readlane_b32 s2, v253, 26
	v_add3_u32 v182, 0, v166, v167
	v_readlane_b32 s48, v251, 4
	v_add_u32_e32 v168, s2, v168
	v_readlane_b32 s2, v253, 19
	v_readlane_b32 s50, v251, 6
	v_readlane_b32 s51, v251, 7
	v_min_i32_e32 v168, s2, v168
	v_cvt_f32_i32_e32 v170, v168
	s_mov_b64 s[74:75], s[50:51]
	s_add_u32 s2, s74, s12
	s_addc_u32 s14, s75, s13
	v_div_scale_f32 v168, s[8:9], v170, v170, 1.0
	v_rcp_f32_e32 v169, v168
	v_div_scale_f32 v171, vcc, 1.0, v170, 1.0
	s_ashr_i32 s8, s17, 2
	v_fma_f32 v172, -v168, v169, 1.0
	v_fmac_f32_e32 v169, v172, v169
	v_mul_f32_e32 v172, v171, v169
	v_fma_f32 v173, -v168, v172, v171
	v_fmac_f32_e32 v172, v173, v169
	v_fma_f32 v168, -v168, v172, v171
	v_div_fmas_f32 v171, v168, v169, v172
	ds_read_b128 v[166:169], v182 offset:4080
	v_div_fixup_f32 v183, v171, v170, 1.0
	ds_read_b128 v[170:173], v182 offset:4096
	ds_read_b128 v[174:177], v182 offset:4112
	ds_read_b128 v[178:181], v182 offset:4128
	s_mov_b64 s[10:11], 0x11101000
	v_readlane_b32 s49, v251, 5
	s_waitcnt lgkmcnt(3)
	v_lshlrev_b32_e32 v184, 16, v166
	v_fma_f32 v160, v183, v160, -v184
	v_and_b32_e32 v166, 0xffff0000, v166
	v_fma_f32 v161, v183, v161, -v166
	v_cvt_pk_bf16_f32 v166, v160, v161
	v_lshlrev_b32_e32 v160, 16, v167
	v_fma_f32 v158, v183, v158, -v160
	v_and_b32_e32 v160, 0xffff0000, v167
	v_fma_f32 v159, v183, v159, -v160
	v_cvt_pk_bf16_f32 v167, v158, v159
	v_lshlrev_b32_e32 v158, 16, v168
	v_fma_f32 v156, v183, v156, -v158
	v_and_b32_e32 v158, 0xffff0000, v168
	v_fma_f32 v157, v183, v157, -v158
	v_cvt_pk_bf16_f32 v168, v156, v157
	v_lshlrev_b32_e32 v156, 16, v169
	v_fma_f32 v154, v183, v154, -v156
	v_and_b32_e32 v156, 0xffff0000, v169
	v_fma_f32 v155, v183, v155, -v156
	v_cvt_pk_bf16_f32 v169, v154, v155
	s_waitcnt lgkmcnt(2)
	v_lshlrev_b32_e32 v154, 16, v170
	v_fma_f32 v152, v183, v152, -v154
	v_and_b32_e32 v154, 0xffff0000, v170
	v_fma_f32 v153, v183, v153, -v154
	v_cvt_pk_bf16_f32 v152, v152, v153
	v_lshlrev_b32_e32 v153, 16, v171
	v_fma_f32 v150, v183, v150, -v153
	v_and_b32_e32 v153, 0xffff0000, v171
	v_fma_f32 v151, v183, v151, -v153
	v_cvt_pk_bf16_f32 v153, v150, v151
	v_lshlrev_b32_e32 v150, 16, v172
	v_fma_f32 v148, v183, v148, -v150
	v_and_b32_e32 v150, 0xffff0000, v172
	v_fma_f32 v149, v183, v149, -v150
	v_cvt_pk_bf16_f32 v154, v148, v149
	v_lshlrev_b32_e32 v148, 16, v173
	v_fma_f32 v146, v183, v146, -v148
	v_and_b32_e32 v148, 0xffff0000, v173
	v_fma_f32 v147, v183, v147, -v148
	v_cvt_pk_bf16_f32 v155, v146, v147
	s_waitcnt lgkmcnt(1)
	v_lshlrev_b32_e32 v146, 16, v174
	v_fma_f32 v144, v183, v144, -v146
	v_and_b32_e32 v146, 0xffff0000, v174
	v_fma_f32 v145, v183, v145, -v146
	v_cvt_pk_bf16_f32 v144, v144, v145
	v_lshlrev_b32_e32 v145, 16, v175
	v_fma_f32 v142, v183, v142, -v145
	v_and_b32_e32 v145, 0xffff0000, v175
	v_fma_f32 v143, v183, v143, -v145
	v_cvt_pk_bf16_f32 v145, v142, v143
	v_lshlrev_b32_e32 v142, 16, v176
	v_fma_f32 v140, v183, v140, -v142
	v_and_b32_e32 v142, 0xffff0000, v176
	v_fma_f32 v141, v183, v141, -v142
	v_cvt_pk_bf16_f32 v146, v140, v141
	v_lshlrev_b32_e32 v140, 16, v177
	v_fma_f32 v138, v183, v138, -v140
	v_and_b32_e32 v140, 0xffff0000, v177
	v_fma_f32 v139, v183, v139, -v140
	v_cvt_pk_bf16_f32 v147, v138, v139
	s_waitcnt lgkmcnt(0)
	v_lshlrev_b32_e32 v138, 16, v178
	v_fma_f32 v136, v183, v136, -v138
	v_and_b32_e32 v138, 0xffff0000, v178
	v_fma_f32 v137, v183, v137, -v138
	v_cvt_pk_bf16_f32 v136, v136, v137
	v_lshlrev_b32_e32 v137, 16, v179
	v_fma_f32 v134, v183, v134, -v137
	v_and_b32_e32 v137, 0xffff0000, v179
	v_fma_f32 v135, v183, v135, -v137
	v_cvt_pk_bf16_f32 v137, v134, v135
	v_lshlrev_b32_e32 v134, 16, v180
	v_fma_f32 v132, v183, v132, -v134
	v_and_b32_e32 v134, 0xffff0000, v180
	v_fma_f32 v133, v183, v133, -v134
	v_cvt_pk_bf16_f32 v138, v132, v133
	v_lshlrev_b32_e32 v132, 16, v181
	v_fma_f32 v130, v183, v130, -v132
	v_and_b32_e32 v132, 0xffff0000, v181
	v_fma_f32 v131, v183, v131, -v132
	v_and_or_b32 v142, s8, -16, v165
	v_cvt_pk_bf16_f32 v139, v130, v131
	v_mul_lo_u32 v130, v142, s33
	v_and_b32_e32 v131, 48, v164
	v_add3_u32 v143, 0, v130, v131
	ds_write_b128 v182, v[166:169] offset:40960
	ds_write_b128 v182, v[152:155] offset:40976
	ds_write_b128 v182, v[144:147] offset:40992
	ds_write_b128 v182, v[136:139] offset:41008
	s_waitcnt lgkmcnt(0)
	s_barrier
	ds_read_b128 v[134:137], v143 offset:40960
	ds_read_b128 v[130:133], v143 offset:41024
	s_waitcnt vmcnt(31) lgkmcnt(1)
	v_mfma_f32_16x16x32_bf16 v[122:125], v[122:125], v[134:137], 0
	v_readlane_b32 s8, v253, 30
	v_mov_b32_e32 v164, v218
	v_readlane_b32 s52, v251, 8
	s_waitcnt vmcnt(30) lgkmcnt(0)
	v_mfma_f32_16x16x32_bf16 v[138:141], v[118:121], v[130:133], v[122:125]
	s_nop 2
	ds_read_b128 v[122:125], v143 offset:41088
	ds_read_b128 v[118:121], v143 offset:41152
	v_readlane_b32 s53, v251, 9
	v_readlane_b32 s54, v251, 10
	s_waitcnt vmcnt(29) lgkmcnt(1)
	v_mfma_f32_16x16x32_bf16 v[114:117], v[114:117], v[122:125], v[138:141]
	v_readlane_b32 s55, v251, 11
	v_readlane_b32 s56, v251, 12
	v_readlane_b32 s57, v251, 13
	s_waitcnt vmcnt(28) lgkmcnt(0)
	v_mfma_f32_16x16x32_bf16 v[110:113], v[110:113], v[118:121], v[114:117]
	v_readlane_b32 s58, v251, 14
	v_readlane_b32 s59, v251, 15
	v_readlane_b32 s60, v251, 16
	s_waitcnt vmcnt(1)
	v_mfma_f32_16x16x32_bf16 v[114:117], v[126:129], v[134:137], 0
	v_readlane_b32 s61, v251, 17
	v_readlane_b32 s62, v251, 18
	v_readlane_b32 s63, v251, 19
	v_mfma_f32_16x16x32_bf16 v[106:109], v[106:109], v[130:133], v[114:117]
	v_mfma_f32_16x16x32_bf16 v[98:101], v[98:101], v[134:137], 0
	s_nop 2
	v_add_u32_e32 v114, s8, v142
	v_mfma_f32_16x16x32_bf16 v[102:105], v[102:105], v[122:125], v[106:109]
	s_nop 2
	v_mov_b64_e32 v[106:107], s[24:25]
	v_mad_i64_i32 v[106:107], s[8:9], v114, s70, v[106:107]
	v_mfma_f32_16x16x32_bf16 v[86:89], v[86:89], v[134:137], 0
	v_readlane_b32 s8, v253, 21
	s_lshl_b32 s28, s8, 1
	v_lshl_add_u64 v[106:107], v[106:107], 0, s[28:29]
	v_mfma_f32_16x16x32_bf16 v[96:99], v[94:97], v[130:133], v[98:101]
	v_lshlrev_b32_e32 v108, 3, v163
	v_mov_b32_e32 v109, v33
	s_mov_b32 s9, 0x11101000
	v_lshl_add_u64 v[100:101], v[106:107], 0, v[108:109]
	v_mfma_f32_16x16x32_bf16 v[84:87], v[82:85], v[130:133], v[86:89]
	s_lshl_b32 s8, s8, 2
	v_lshl_add_u64 v[94:95], v[100:101], 0, s[10:11]
	s_add_u32 s10, s2, s8
	v_mfma_f32_16x16x32_bf16 v[90:93], v[90:93], v[122:125], v[96:99]
	s_addc_u32 s11, s14, 0
	v_readlane_b32 s8, v253, 28
	s_or_b32 s8, s8, s16
	v_add_co_u32_e32 v96, vcc, s9, v100
	v_mfma_f32_16x16x32_bf16 v[78:81], v[78:81], v[122:125], v[84:87]
	s_nop 0
	v_addc_co_u32_e32 v97, vcc, 0, v101, vcc
	global_load_dwordx2 v[98:99], v[94:95], off offset:32
	global_load_dwordx2 v[100:101], v[94:95], off offset:64
	global_load_dwordx2 v[106:107], v[94:95], off offset:96
	global_load_dwordx2 v[108:109], v[94:95], off offset:128
	global_load_dwordx2 v[88:89], v[96:97], off
	global_load_dwordx2 v[114:115], v[94:95], off offset:160
	global_load_dwordx2 v[116:117], v[94:95], off offset:192
	global_load_dwordx2 v[82:83], v[94:95], off offset:224
	global_load_dwordx4 v[84:87], v32, s[10:11]
	global_load_dwordx4 v[188:191], v32, s[10:11] offset:64
	global_load_dwordx4 v[192:195], v32, s[10:11] offset:128
	global_load_dwordx4 v[196:199], v32, s[10:11] offset:192
	global_load_dwordx4 v[200:203], v32, s[10:11] offset:256
	global_load_dwordx4 v[210:213], v32, s[10:11] offset:320
	global_load_dwordx4 v[214:217], v32, s[10:11] offset:384
	global_load_dwordx4 v[228:231], v32, s[10:11] offset:448
	v_mfma_f32_16x16x32_bf16 v[74:77], v[74:77], v[134:137], 0
	v_readlane_b32 s9, v252, 29
	s_add_u32 s8, s9, s8
	v_readlane_b32 s9, v252, 30
	v_mfma_f32_16x16x32_bf16 v[62:65], v[62:65], v[134:137], 0
	s_addc_u32 s9, s9, 0
	v_mfma_f32_16x16x32_bf16 v[70:73], v[70:73], v[130:133], v[74:77]
	v_mfma_f32_16x16x32_bf16 v[58:61], v[58:61], v[130:133], v[62:65]
	s_waitcnt vmcnt(4)
	s_nop 0
	v_lshlrev_b32_e32 v75, 16, v88
	v_mfma_f32_16x16x32_bf16 v[66:69], v[66:69], v[122:125], v[70:73]
	s_nop 0
	v_and_b32_e32 v64, 0xffff0000, v89
	s_waitcnt vmcnt(0)
	v_mul_f32_e32 v74, v110, v84
	v_mul_f32_e32 v70, v111, v85
	v_and_b32_e32 v71, 0xffff0000, v88
	v_mul_f32_e32 v70, v70, v71
	v_mul_f32_e32 v71, v112, v86
	v_lshlrev_b32_e32 v72, 16, v89
	v_mul_f32_e32 v63, v113, v87
	v_mul_f32_e32 v74, v74, v75
	v_cvt_pk_bf16_f32 v70, v74, v70
	v_mul_f32_e32 v62, v71, v72
	v_mfma_f32_16x16x32_bf16 v[54:57], v[54:57], v[122:125], v[58:61]
	s_nop 2
	v_mul_f32_e32 v58, v63, v64
	v_cvt_pk_bf16_f32 v71, v62, v58
	global_store_dwordx2 v[96:97], v[70:71], off
	v_mov_b64_e32 v[58:59], v[188:189]
	v_mov_b64_e32 v[60:61], v[190:191]
	v_mfma_f32_16x16x32_bf16 v[50:53], v[50:53], v[134:137], 0
	v_lshlrev_b32_e32 v62, 16, v98
	v_mfma_f32_16x16x32_bf16 v[28:31], v[28:31], v[118:121], v[102:105]
	v_mfma_f32_16x16x32_bf16 v[46:49], v[46:49], v[130:133], v[50:53]
	v_mfma_f32_16x16x32_bf16 v[42:45], v[42:45], v[122:125], v[46:49]
	s_nop 4
	v_mul_f32_e32 v28, v28, v58
	v_mul_f32_e32 v29, v29, v59
	v_and_b32_e32 v58, 0xffff0000, v98
	v_mul_f32_e32 v28, v28, v62
	v_mul_f32_e32 v29, v29, v58
	v_cvt_pk_bf16_f32 v50, v28, v29
	v_mul_f32_e32 v28, v30, v60
	v_lshlrev_b32_e32 v29, 16, v99
	v_mul_f32_e32 v46, v28, v29
	v_mul_f32_e32 v47, v31, v61
	v_mfma_f32_16x16x32_bf16 v[28:31], v[38:41], v[134:137], 0
	v_and_b32_e32 v48, 0xffff0000, v99
	v_mul_f32_e32 v38, v47, v48
	v_cvt_pk_bf16_f32 v51, v46, v38
	global_store_dwordx2 v[94:95], v[50:51], off offset:32
	v_mfma_f32_16x16x32_bf16 v[28:31], v[34:37], v[130:133], v[28:31]
	v_mov_b64_e32 v[34:35], v[192:193]
	v_mov_b64_e32 v[36:37], v[194:195]
	v_lshlrev_b32_e32 v38, 16, v100
	v_and_b32_e32 v39, 0xffff0000, v100
	v_mfma_f32_16x16x32_bf16 v[24:27], v[24:27], v[118:121], v[90:93]
	v_lshlrev_b32_e32 v40, 16, v101
	v_and_b32_e32 v41, 0xffff0000, v101
	v_mov_b32_e32 v131, v33
	v_mfma_f32_16x16x32_bf16 v[16:19], v[16:19], v[118:121], v[78:81]
	v_mfma_f32_16x16x32_bf16 v[20:23], v[20:23], v[118:121], v[66:69]
	s_nop 1
	v_mul_f32_e32 v24, v24, v34
	v_mul_f32_e32 v25, v25, v35
	v_mul_f32_e32 v26, v26, v36
	v_mul_f32_e32 v27, v27, v37
	v_mul_f32_e32 v24, v24, v38
	v_mul_f32_e32 v25, v25, v39
	v_mul_f32_e32 v26, v26, v40
	v_mul_f32_e32 v27, v27, v41
	v_cvt_pk_bf16_f32 v24, v24, v25
	v_cvt_pk_bf16_f32 v25, v26, v27
	global_store_dwordx2 v[94:95], v[24:25], off offset:64
	v_mov_b64_e32 v[24:25], v[196:197]
	v_mov_b64_e32 v[26:27], v[198:199]
	v_lshlrev_b32_e32 v34, 16, v106
	v_and_b32_e32 v35, 0xffff0000, v106
	v_lshlrev_b32_e32 v36, 16, v107
	v_and_b32_e32 v37, 0xffff0000, v107
	v_mfma_f32_16x16x32_bf16 v[12:15], v[12:15], v[118:121], v[54:57]
	v_mul_f32_e32 v16, v16, v24
	v_mul_f32_e32 v17, v17, v25
	v_mul_f32_e32 v18, v18, v26
	v_mul_f32_e32 v19, v19, v27
	v_mul_f32_e32 v16, v16, v34
	v_mul_f32_e32 v17, v17, v35
	v_mul_f32_e32 v18, v18, v36
	v_mul_f32_e32 v19, v19, v37
	v_cvt_pk_bf16_f32 v16, v16, v17
	v_cvt_pk_bf16_f32 v17, v18, v19
	global_store_dwordx2 v[94:95], v[16:17], off offset:96
	v_mov_b64_e32 v[16:17], v[200:201]
	v_mov_b64_e32 v[18:19], v[202:203]
	v_lshlrev_b32_e32 v24, 16, v108
	v_and_b32_e32 v25, 0xffff0000, v108
	v_lshlrev_b32_e32 v26, 16, v109
	v_and_b32_e32 v27, 0xffff0000, v109
	v_mfma_f32_16x16x32_bf16 v[8:11], v[8:11], v[118:121], v[42:45]
	v_mul_f32_e32 v16, v20, v16
	v_mul_f32_e32 v17, v21, v17
	v_mul_f32_e32 v18, v22, v18
	v_mul_f32_e32 v19, v23, v19
	v_mul_f32_e32 v16, v16, v24
	v_mul_f32_e32 v17, v17, v25
	v_mul_f32_e32 v18, v18, v26
	v_mul_f32_e32 v19, v19, v27
	v_cvt_pk_bf16_f32 v16, v16, v17
	v_cvt_pk_bf16_f32 v17, v18, v19
	global_store_dwordx2 v[94:95], v[16:17], off offset:128
	v_mov_b64_e32 v[16:17], v[210:211]
	v_mov_b64_e32 v[18:19], v[212:213]
	v_lshlrev_b32_e32 v20, 16, v114
	v_and_b32_e32 v21, 0xffff0000, v114
	v_lshlrev_b32_e32 v22, 16, v115
	v_and_b32_e32 v23, 0xffff0000, v115
	v_mfma_f32_16x16x32_bf16 v[4:7], v[4:7], v[122:125], v[28:31]
	v_mul_f32_e32 v12, v12, v16
	v_mul_f32_e32 v13, v13, v17
	v_mul_f32_e32 v14, v14, v18
	v_mul_f32_e32 v15, v15, v19
	v_mul_f32_e32 v12, v12, v20
	v_mul_f32_e32 v13, v13, v21
	v_mul_f32_e32 v14, v14, v22
	v_mul_f32_e32 v15, v15, v23
	v_cvt_pk_bf16_f32 v12, v12, v13
	v_cvt_pk_bf16_f32 v13, v14, v15
	global_store_dwordx2 v[94:95], v[12:13], off offset:160
	v_mov_b64_e32 v[12:13], v[214:215]
	v_mov_b64_e32 v[14:15], v[216:217]
	v_lshlrev_b32_e32 v16, 16, v116
	v_and_b32_e32 v17, 0xffff0000, v116
	v_lshlrev_b32_e32 v18, 16, v117
	v_and_b32_e32 v19, 0xffff0000, v117
	v_mfma_f32_16x16x32_bf16 v[0:3], v[0:3], v[118:121], v[4:7]
	v_mul_f32_e32 v8, v8, v12
	v_mul_f32_e32 v9, v9, v13
	v_mul_f32_e32 v10, v10, v14
	v_mul_f32_e32 v11, v11, v15
	v_mul_f32_e32 v8, v8, v16
	v_mul_f32_e32 v9, v9, v17
	v_mul_f32_e32 v10, v10, v18
	v_mul_f32_e32 v11, v11, v19
	v_cvt_pk_bf16_f32 v8, v8, v9
	v_cvt_pk_bf16_f32 v9, v10, v11
	global_store_dwordx2 v[94:95], v[8:9], off offset:192
	v_mov_b64_e32 v[8:9], v[228:229]
	v_mov_b64_e32 v[10:11], v[230:231]
	v_lshlrev_b32_e32 v4, 16, v82
	v_and_b32_e32 v5, 0xffff0000, v82
	v_lshlrev_b32_e32 v6, 16, v83
	v_and_b32_e32 v7, 0xffff0000, v83
	v_mul_f32_e32 v0, v0, v8
	v_mul_f32_e32 v1, v1, v9
	v_mul_f32_e32 v2, v2, v10
	v_mul_f32_e32 v3, v3, v11
	v_mul_f32_e32 v0, v0, v4
	v_mul_f32_e32 v1, v1, v5
	v_mul_f32_e32 v2, v2, v6
	v_mul_f32_e32 v3, v3, v7
	v_cvt_pk_bf16_f32 v0, v0, v1
	v_cvt_pk_bf16_f32 v1, v2, v3
	global_store_dwordx2 v[94:95], v[0:1], off offset:224
	s_barrier
	s_nop 0
	v_and_b32_e32 v165, 15, v164
	v_bfe_u32 v163, v164, 4, 2
	v_lshlrev_b32_e32 v32, 8, v165
	v_lshl_add_u64 v[0:1], s[8:9], 0, v[32:33]
	v_lshlrev_b32_e32 v32, 4, v163
	v_lshl_add_u64 v[0:1], v[0:1], 0, v[32:33]
	v_readlane_b32 s8, v253, 35
	v_readlane_b32 s9, v253, 36
	v_lshlrev_b32_e32 v130, 4, v165
	v_mov_b32_e32 v131, v33
	s_nop 1
	v_lshl_add_u64 v[136:137], s[8:9], 0, v[130:131]
	v_add_u32_e32 v134, 0, v130
	s_movk_i32 s8, 0x8f0
	v_cmp_gt_i32_e32 vcc, s8, v164
	s_and_saveexec_b64 s[10:11], vcc
	v_readlane_b32 s86, v254, 59
	v_readlane_b32 s84, v254, 61
	v_readlane_b32 s87, v254, 60
	v_readlane_b32 s85, v254, 62
	s_cbranch_execz .LBB0_1251
	v_ashrrev_i32_e32 v135, 4, v164
	v_readlane_b32 s8, v253, 38
	v_mov_b32_e32 v232, 0
	v_mov_b32_e32 v233, 0
	v_cmp_lt_i32_e32 vcc, s8, v135
	v_mov_b32_e32 v234, 0
	v_mov_b32_e32 v235, 0
	s_and_saveexec_b64 s[12:13], vcc
	s_cbranch_execz .LBB0_1250
	v_readlane_b32 s8, v253, 37
	s_nop 1
	v_add_u32_e32 v232, s8, v135
	v_mad_i64_i32 v[232:233], s[8:9], v232, s70, v[136:137]
	global_load_dwordx4 v[232:235], v[232:233], off

.LBB0_1267:
	s_or_b64 exec, exec, s[10:11]
	s_movk_i32 s8, 0x1000
	v_add_co_u32_e32 v2, vcc, s8, v0
	s_movk_i32 s8, 0x3000
	s_nop 0
	v_addc_co_u32_e32 v3, vcc, 0, v1, vcc
	v_add_co_u32_e32 v12, vcc, s1, v0
	global_load_dwordx4 v[114:117], v[0:1], off
	global_load_dwordx4 v[110:113], v[0:1], off offset:64
	global_load_dwordx4 v[106:109], v[0:1], off offset:128
	global_load_dwordx4 v[102:105], v[0:1], off offset:192
	v_addc_co_u32_e32 v13, vcc, 0, v1, vcc
	v_add_co_u32_e32 v4, vcc, s8, v0
	s_movk_i32 s8, 0x4000
	s_nop 0
	v_addc_co_u32_e32 v5, vcc, 0, v1, vcc
	v_add_co_u32_e32 v6, vcc, s8, v0
	s_movk_i32 s8, 0x5000
	s_nop 0
	v_addc_co_u32_e32 v7, vcc, 0, v1, vcc
	global_load_dwordx4 v[122:125], v[2:3], off offset:64
	global_load_dwordx4 v[118:121], v[2:3], off offset:128
	global_load_dwordx4 v[98:101], v[12:13], off
	global_load_dwordx4 v[94:97], v[12:13], off offset:64
	global_load_dwordx4 v[90:93], v[12:13], off offset:128
	global_load_dwordx4 v[20:23], v[12:13], off offset:192
	global_load_dwordx4 v[38:41], v[2:3], off offset:192
	global_load_dwordx4 v[78:81], v[4:5], off offset:64
	global_load_dwordx4 v[74:77], v[4:5], off offset:128
	global_load_dwordx4 v[16:19], v[4:5], off offset:192
	global_load_dwordx4 v[82:85], v[6:7], off offset:-4096
	global_load_dwordx4 v[70:73], v[6:7], off
	global_load_dwordx4 v[66:69], v[6:7], off offset:64
	global_load_dwordx4 v[58:61], v[6:7], off offset:128
	v_add_co_u32_e32 v8, vcc, s8, v0
	s_movk_i32 s8, 0x6000
	s_nop 0
	v_addc_co_u32_e32 v9, vcc, 0, v1, vcc
	v_add_co_u32_e32 v2, vcc, s8, v0
	global_load_dwordx4 v[62:65], v[8:9], off offset:64
	global_load_dwordx4 v[50:53], v[8:9], off offset:128
	v_addc_co_u32_e32 v3, vcc, 0, v1, vcc
	v_add_co_u32_e32 v14, vcc, 0x7000, v0
	global_load_dwordx4 v[34:37], v[6:7], off offset:192
	global_load_dwordx4 v[86:89], v[2:3], off offset:-4096
	global_load_dwordx4 v[54:57], v[2:3], off
	global_load_dwordx4 v[46:49], v[2:3], off offset:64
	global_load_dwordx4 v[42:45], v[2:3], off offset:128
	global_load_dwordx4 v[24:27], v[2:3], off offset:192
	v_addc_co_u32_e32 v15, vcc, 0, v1, vcc
	global_load_dwordx4 v[28:31], v[8:9], off offset:192
	s_nop 0
	global_load_dwordx4 v[8:11], v[14:15], off
	global_load_dwordx4 v[4:7], v[14:15], off offset:64
	global_load_dwordx4 v[0:3], v[14:15], off offset:128
	global_load_dwordx4 v[126:129], v[12:13], off offset:-4096
	s_nop 0
	global_load_dwordx4 v[12:15], v[14:15], off offset:192
	v_readlane_b32 s8, v253, 35
	v_lshlrev_b32_e32 v130, 4, v165
	v_readlane_b32 s9, v253, 36
	v_readfirstlane_b32 s15, v164
	v_add_u32_e32 v134, 0, v130
	v_lshl_add_u64 v[136:137], s[8:9], 0, v[130:131]
	s_movk_i32 s8, 0x8f0
	s_waitcnt vmcnt(32)
	s_movk_i32 s8, 0x8f0
	v_cmp_gt_i32_e32 vcc, s8, v164
	s_and_saveexec_b64 s[10:11], vcc
	ds_write_b128 v204, v[232:235]
	s_or_b64 exec, exec, s[10:11]
	s_movk_i32 s8, 0x6f0
	v_cmp_gt_i32_e32 vcc, s8, v164
	s_and_saveexec_b64 s[10:11], vcc
	ds_write_b128 v205, v[188:191]
	s_or_b64 exec, exec, s[10:11]
	s_movk_i32 s8, 0x4f0
	v_cmp_gt_i32_e32 vcc, s8, v164
	s_and_saveexec_b64 s[10:11], vcc
	ds_write_b128 v206, v[192:195]
	s_or_b64 exec, exec, s[10:11]
	s_movk_i32 s8, 0x2f0
	v_cmp_gt_i32_e32 vcc, s8, v164
	s_and_saveexec_b64 s[10:11], vcc
	ds_write_b128 v207, v[196:199]
	s_or_b64 exec, exec, s[10:11]
	s_movk_i32 s8, 0xf0
	v_cmp_gt_i32_e32 vcc, s8, v164
	s_and_saveexec_b64 s[10:11], vcc
	ds_write_b128 v208, v[200:203]
	s_or_b64 exec, exec, s[10:11]
	v_ashrrev_i32_e32 v168, 2, v164
	v_lshlrev_b32_e32 v130, 6, v164
	v_mul_lo_u32 v166, v168, s33
	v_and_b32_e32 v167, 0xc0, v130
	v_readlane_b32 s8, v254, 56
	v_mov_b32_e32 v130, 0
	v_mov_b32_e32 v131, v130
	v_add3_u32 v169, v166, v167, s8
	v_readlane_b32 s8, v253, 27
	v_mov_b32_e32 v160, v130
	v_mov_b32_e32 v161, v130
	v_mov_b32_e32 v158, v130
	v_mov_b32_e32 v159, v130
	v_mov_b32_e32 v156, v130
	v_mov_b32_e32 v157, v130
	v_mov_b32_e32 v154, v130
	v_mov_b32_e32 v155, v130
	v_mov_b32_e32 v152, v130
	v_mov_b32_e32 v153, v130
	v_mov_b32_e32 v150, v130
	v_mov_b32_e32 v151, v130
	v_mov_b32_e32 v148, v130
	v_mov_b32_e32 v149, v130
	v_mov_b32_e32 v146, v130
	v_mov_b32_e32 v147, v130
	v_mov_b32_e32 v144, v130
	v_mov_b32_e32 v145, v130
	v_mov_b32_e32 v142, v130
	v_mov_b32_e32 v143, v130
	v_mov_b32_e32 v140, v130
	v_mov_b32_e32 v141, v130
	v_mov_b32_e32 v138, v130
	v_mov_b32_e32 v139, v130
	v_mov_b32_e32 v136, v130
	v_mov_b32_e32 v137, v130
	v_mov_b32_e32 v134, v130
	v_mov_b32_e32 v135, v130
	v_mov_b32_e32 v132, v130
	v_mov_b32_e32 v133, v130
	s_waitcnt lgkmcnt(0)
	s_barrier
